# plus: top-k bisection loops exit early over rows beyond the admissible key range (dead -inf rows never count while >=256 finite keys)
# speedup vs baseline: 1.0325x; 1.0056x over previous
; __device__ __forceinline__ void topk_list(const unsigned (&uk)[32], LAS int* list, LAS float* listr, LAS unsigned* listT, const GAS f32x4* sak, int lane) {
;     unsigned T = 0u;
;     ...
;         const unsigned cand = T | (1u << bit);
;         int c = 0;
; #pragma unroll
;         for (int rr = 0; rr < 32; ++rr) c += __builtin_popcountll(__builtin_amdgcn_ballot_w64(uk[rr] >= cand));
;         if (c >= 256) T = cand;
;         if (c == 256) break;
;     }
.LBB0_747:
	v_lshlrev_b32_e64 v11, v10, 1
	v_or_b32_e32 v11, v11, v85
	v_cmp_ge_u32_e32 vcc, v9, v11
	s_bcnt1_i32_b64 s0, vcc
	v_cmp_ge_u32_e32 vcc, v8, v11
	s_bcnt1_i32_b64 s1, vcc
	s_add_i32 s0, s0, s1
	v_cmp_ge_u32_e32 vcc, v7, v11
	s_bcnt1_i32_b64 s1, vcc
	s_add_i32 s0, s0, s1
	v_cmp_ge_u32_e32 vcc, v6, v11
	s_bcnt1_i32_b64 s1, vcc
	s_add_i32 s0, s0, s1
	s_cmpk_le_u32 s81, 0x100
	s_cbranch_scc1 .Lbis0_tail
	v_cmp_ge_u32_e32 vcc, v13, v11
	s_bcnt1_i32_b64 s1, vcc
	s_add_i32 s0, s0, s1
	v_cmp_ge_u32_e32 vcc, v15, v11
	s_bcnt1_i32_b64 s1, vcc
	s_add_i32 s0, s0, s1
	v_cmp_ge_u32_e32 vcc, v16, v11
	s_bcnt1_i32_b64 s1, vcc
	s_add_i32 s0, s0, s1
	v_cmp_ge_u32_e32 vcc, v18, v11
	s_bcnt1_i32_b64 s1, vcc
	s_add_i32 s0, s0, s1
	s_cmpk_le_u32 s81, 0x200
	s_cbranch_scc1 .Lbis0_tail
	v_cmp_ge_u32_e32 vcc, v145, v11
	s_bcnt1_i32_b64 s1, vcc
	s_add_i32 s0, s0, s1
	v_cmp_ge_u32_e32 vcc, v144, v11
	s_bcnt1_i32_b64 s1, vcc
	s_add_i32 s0, s0, s1
	v_cmp_ge_u32_e32 vcc, v143, v11
	s_bcnt1_i32_b64 s1, vcc
	s_add_i32 s0, s0, s1
	v_cmp_ge_u32_e32 vcc, v142, v11
	s_bcnt1_i32_b64 s1, vcc
	s_add_i32 s0, s0, s1
	s_cmpk_le_u32 s81, 0x300
	s_cbranch_scc1 .Lbis0_tail
	v_cmp_ge_u32_e32 vcc, v159, v11
	s_bcnt1_i32_b64 s1, vcc
	s_add_i32 s0, s0, s1
	v_cmp_ge_u32_e32 vcc, v158, v11
	s_bcnt1_i32_b64 s1, vcc
	s_add_i32 s0, s0, s1
	v_cmp_ge_u32_e32 vcc, v156, v11
	s_bcnt1_i32_b64 s1, vcc
	s_add_i32 s0, s0, s1
	v_cmp_ge_u32_e32 vcc, v153, v11
	s_bcnt1_i32_b64 s1, vcc
	s_add_i32 s0, s0, s1
	s_cmpk_le_u32 s81, 0x400
	s_cbranch_scc1 .Lbis0_tail
	v_cmp_ge_u32_e32 vcc, v167, v11
	s_bcnt1_i32_b64 s1, vcc
	s_add_i32 s0, s0, s1
	v_cmp_ge_u32_e32 vcc, v166, v11
	s_bcnt1_i32_b64 s1, vcc
	s_add_i32 s0, s0, s1
	v_cmp_ge_u32_e32 vcc, v165, v11
	s_bcnt1_i32_b64 s1, vcc
	s_add_i32 s0, s0, s1
	v_cmp_ge_u32_e32 vcc, v164, v11
	s_bcnt1_i32_b64 s1, vcc
	s_add_i32 s0, s0, s1
	s_cmpk_le_u32 s81, 0x500
	s_cbranch_scc1 .Lbis0_tail
	v_cmp_ge_u32_e32 vcc, v171, v11
	s_bcnt1_i32_b64 s1, vcc
	s_add_i32 s0, s0, s1
	v_cmp_ge_u32_e32 vcc, v170, v11
	s_bcnt1_i32_b64 s1, vcc
	s_add_i32 s0, s0, s1
	v_cmp_ge_u32_e32 vcc, v169, v11
	s_bcnt1_i32_b64 s1, vcc
	s_add_i32 s0, s0, s1
	v_cmp_ge_u32_e32 vcc, v168, v11
	s_bcnt1_i32_b64 s1, vcc
	s_add_i32 s0, s0, s1
	s_cmpk_le_u32 s81, 0x600
	s_cbranch_scc1 .Lbis0_tail
	v_cmp_ge_u32_e32 vcc, v175, v11
	s_bcnt1_i32_b64 s1, vcc
	s_add_i32 s0, s0, s1
	v_cmp_ge_u32_e32 vcc, v174, v11
	s_bcnt1_i32_b64 s1, vcc
	s_add_i32 s0, s0, s1
	v_cmp_ge_u32_e32 vcc, v173, v11
	s_bcnt1_i32_b64 s1, vcc
	s_add_i32 s0, s0, s1
	v_cmp_ge_u32_e32 vcc, v172, v11
	s_bcnt1_i32_b64 s1, vcc
	s_add_i32 s0, s0, s1
	s_cmpk_le_u32 s81, 0x700
	s_cbranch_scc1 .Lbis0_tail
	v_cmp_ge_u32_e32 vcc, v100, v11
	s_bcnt1_i32_b64 s1, vcc
	s_add_i32 s0, s0, s1
	v_cmp_ge_u32_e32 vcc, v89, v11
	s_bcnt1_i32_b64 s1, vcc
	s_add_i32 s0, s0, s1
	v_cmp_ge_u32_e32 vcc, v88, v11
	s_bcnt1_i32_b64 s1, vcc
	s_add_i32 s0, s0, s1
	v_cmp_ge_u32_e32 vcc, v38, v11
	s_bcnt1_i32_b64 s1, vcc
	s_add_i32 s0, s0, s1
; __device__ __forceinline__ void topk_list(const unsigned (&uk)[32], LAS int* list, LAS float* listr, LAS unsigned* listT, const GAS f32x4* sak, int lane) {
;     ...
;         if (c >= 256) T = cand;
;         if (c == 256) break;
;     }
;     int cgt = 0;
; #pragma unroll
;     for (int rr = 0; rr < 32; ++rr) cgt += __builtin_popcountll(__builtin_amdgcn_ballot_w64(uk[rr] > T));
;     const int need_eq = 256 - cgt;
;     int base = 0, eqseen = 0;
; #pragma unroll
;     for (int rr = 0; rr < 32; ++rr) {
;         const bool gt = uk[rr] > T, eq = uk[rr] == T;
;         const unsigned long long meq = __builtin_amdgcn_ballot_w64(eq);
;         const int erank = eqseen + (int)__builtin_amdgcn_mbcnt_hi((unsigned)(meq >> 32), __builtin_amdgcn_mbcnt_lo((unsigned)meq, 0u));
;         const bool sel = gt || (eq && erank < need_eq);
;         const unsigned long long ms = __builtin_amdgcn_ballot_w64(sel);
;         const int pos = base + (int)__builtin_amdgcn_mbcnt_hi((unsigned)(ms >> 32), __builtin_amdgcn_mbcnt_lo((unsigned)ms, 0u));
;         if (sel) { list[pos] = 64 * rr + lane; listT[((pos >> 5) * 4 + (pos & 3)) * 8 + ((pos >> 2) & 7)] = (unsigned)(64 * rr + lane) * 512u; }
.Lbis0_tail:
	s_cmpk_gt_u32 s0, 0xff
	s_cselect_b64 vcc, -1, 0
	s_cmpk_eq_i32 s0, 0x100
	v_cndmask_b32_e32 v85, v85, v11, vcc
	s_cselect_b64 s[0:1], -1, 0
	v_subrev_co_u32_e32 v10, vcc, 1, v10
	s_or_b64 s[0:1], s[0:1], vcc
	s_andn2_b64 vcc, exec, s[0:1]
	s_cbranch_vccnz .LBB0_747
	v_cmp_gt_u32_e32 vcc, v9, v85
	s_bcnt1_i32_b64 s0, vcc
	v_cmp_gt_u32_e32 vcc, v8, v85
	s_bcnt1_i32_b64 s1, vcc
	v_cmp_gt_u32_e32 vcc, v7, v85
	s_bcnt1_i32_b64 s2, vcc
	v_cmp_gt_u32_e32 vcc, v6, v85
	s_add_i32 s0, s0, s1
	s_bcnt1_i32_b64 s3, vcc
	v_cmp_gt_u32_e32 vcc, v13, v85
	s_add_i32 s0, s0, s2
	s_bcnt1_i32_b64 s66, vcc
	v_cmp_gt_u32_e32 vcc, v15, v85
	s_add_i32 s0, s0, s3
	s_bcnt1_i32_b64 s67, vcc
	v_cmp_gt_u32_e32 vcc, v16, v85
	s_add_i32 s0, s0, s66
	s_bcnt1_i32_b64 s68, vcc
	v_cmp_gt_u32_e32 vcc, v18, v85
	s_add_i32 s0, s0, s67
	s_bcnt1_i32_b64 s69, vcc
	v_cmp_gt_u32_e32 vcc, v145, v85
	s_add_i32 s66, s0, s68
	s_bcnt1_i32_b64 s78, vcc
	v_cmp_gt_u32_e32 vcc, v144, v85
	s_add_i32 s66, s66, s69
	s_bcnt1_i32_b64 s79, vcc
	v_cmp_gt_u32_e32 vcc, v143, v85
	s_add_i32 s66, s66, s78
	s_bcnt1_i32_b64 s82, vcc
	v_cmp_gt_u32_e32 vcc, v142, v85
	s_add_i32 s66, s66, s79
	s_bcnt1_i32_b64 s83, vcc
	v_cmp_gt_u32_e32 vcc, v159, v85
	s_add_i32 s66, s66, s82
	s_bcnt1_i32_b64 s84, vcc
	v_cmp_gt_u32_e32 vcc, v158, v85
	s_add_i32 s66, s66, s83
	s_bcnt1_i32_b64 s85, vcc
	v_cmp_gt_u32_e32 vcc, v156, v85
	s_add_i32 s66, s66, s84
	s_bcnt1_i32_b64 s86, vcc
	v_cmp_gt_u32_e32 vcc, v153, v85
	s_add_i32 s66, s66, s85
	s_bcnt1_i32_b64 s87, vcc
	v_cmp_gt_u32_e32 vcc, v167, v85
	s_add_i32 s66, s66, s86
	s_bcnt1_i32_b64 s88, vcc
	v_cmp_gt_u32_e32 vcc, v166, v85
	s_add_i32 s66, s66, s87
	s_bcnt1_i32_b64 s89, vcc
	v_cmp_gt_u32_e32 vcc, v165, v85
	s_add_i32 s66, s66, s88
	s_bcnt1_i32_b64 s90, vcc
	v_cmp_gt_u32_e32 vcc, v164, v85
	s_add_i32 s66, s66, s89
	s_bcnt1_i32_b64 s91, vcc
	v_cmp_gt_u32_e32 vcc, v171, v85
	s_add_i32 s66, s66, s90
	s_bcnt1_i32_b64 s92, vcc
	v_cmp_gt_u32_e32 vcc, v170, v85
	s_add_i32 s66, s66, s91
	s_bcnt1_i32_b64 s93, vcc
	v_cmp_gt_u32_e32 vcc, v169, v85
	s_add_i32 s66, s66, s92
	s_bcnt1_i32_b64 s94, vcc
	v_cmp_gt_u32_e32 vcc, v168, v85
	s_add_i32 s66, s66, s93
	s_bcnt1_i32_b64 s95, vcc
	v_cmp_gt_u32_e32 vcc, v175, v85
	s_add_i32 s66, s66, s94
	s_bcnt1_i32_b64 s96, vcc
	v_cmp_gt_u32_e32 vcc, v174, v85
	s_add_i32 s66, s66, s95
	s_bcnt1_i32_b64 s97, vcc
	v_cmp_gt_u32_e32 vcc, v173, v85
	s_add_i32 s66, s66, s96
	s_bcnt1_i32_b64 s76, vcc
	v_cmp_gt_u32_e32 vcc, v172, v85
	s_add_i32 s66, s66, s97
	s_bcnt1_i32_b64 s77, vcc
	v_cmp_gt_u32_e32 vcc, v100, v85
	s_add_i32 s66, s66, s76
	s_bcnt1_i32_b64 s80, vcc
	v_cmp_gt_u32_e32 vcc, v89, v85
	s_add_i32 s66, s66, s77
	s_bcnt1_i32_b64 s70, vcc
	v_cmp_gt_u32_e32 vcc, v88, v85
	s_add_i32 s66, s66, s80
	s_bcnt1_i32_b64 s71, vcc
	v_cmp_gt_u32_e32 vcc, v38, v85
	s_add_i32 s66, s66, s70
	s_bcnt1_i32_b64 s74, vcc
	s_add_i32 s66, s66, s71
	s_add_i32 s66, s66, s74
	v_cmp_le_u32_e64 s[62:63], v8, v85
	v_cmp_le_u32_e64 s[64:65], v9, v85
	v_cmp_le_u32_e64 s[60:61], v7, v85
	v_cmp_le_u32_e64 s[58:59], v6, v85
	v_cmp_le_u32_e64 s[56:57], v13, v85
	v_cmp_le_u32_e64 s[54:55], v15, v85
	v_cmp_le_u32_e64 s[52:53], v16, v85
	v_cmp_le_u32_e64 s[50:51], v18, v85
	v_cmp_le_u32_e64 s[48:49], v145, v85
	v_cmp_le_u32_e64 s[46:47], v144, v85
	v_cmp_le_u32_e64 s[44:45], v143, v85
	v_cmp_le_u32_e64 s[42:43], v142, v85
	v_cmp_le_u32_e64 s[40:41], v159, v85
	v_cmp_le_u32_e64 s[38:39], v158, v85
	v_cmp_le_u32_e64 s[36:37], v156, v85
	v_cmp_le_u32_e64 s[34:35], v153, v85
	v_cmp_le_u32_e64 s[30:31], v167, v85
	v_cmp_le_u32_e64 s[28:29], v166, v85
	v_cmp_le_u32_e64 s[26:27], v165, v85
	v_cmp_le_u32_e64 s[24:25], v164, v85
	v_cmp_le_u32_e64 s[22:23], v171, v85
	v_cmp_le_u32_e64 s[20:21], v170, v85
	v_cmp_le_u32_e64 s[18:19], v169, v85
	v_cmp_le_u32_e64 s[16:17], v168, v85
	v_cmp_le_u32_e64 s[14:15], v175, v85
	v_cmp_le_u32_e64 s[12:13], v174, v85
	v_cmp_le_u32_e64 s[10:11], v173, v85
	v_cmp_le_u32_e64 s[8:9], v172, v85
	v_cmp_le_u32_e64 s[4:5], v100, v85
	v_cmp_le_u32_e64 s[2:3], v89, v85
	v_cmp_le_u32_e64 s[0:1], v88, v85
	v_cmp_le_u32_e32 vcc, v38, v85
	s_sub_i32 s82, 0x100, s66
	v_cmp_eq_u32_e64 s[68:69], v9, v85
	s_mov_b64 s[78:79], -1
	s_and_saveexec_b64 s[66:67], s[64:65]
	v_mbcnt_lo_u32_b32 v9, s68, 0
	v_mbcnt_hi_u32_b32 v9, s69, v9
	v_cmp_gt_i32_e64 s[64:65], s82, v9
	s_and_b64 s[64:65], s[68:69], s[64:65]
	s_orn2_b64 s[78:79], s[64:65], exec
	s_or_b64 exec, exec, s[66:67]
	v_cndmask_b32_e64 v9, 0, 1, s[78:79]
	v_cmp_ne_u32_e64 s[66:67], 0, v9
	v_lshlrev_b32_e32 v9, 9, v124
	s_and_saveexec_b64 s[64:65], s[78:79]
	s_cbranch_execz .LBB0_752
	v_mbcnt_lo_u32_b32 v10, s66, 0
	v_mbcnt_hi_u32_b32 v10, s67, v10
	v_lshl_add_u32 v11, v10, 2, s33
	ds_write_b32 v11, v124
	v_and_b32_e32 v11, 0x60, v10
	v_lshlrev_b32_e32 v12, 5, v10
	v_lshl_add_u32 v11, v11, 2, s33
	v_and_b32_e32 v12, 0x60, v12
	v_and_b32_e32 v10, 28, v10
	v_add3_u32 v10, v11, v12, v10
	ds_write_b32 v10, v9 offset:4096

; __device__ __forceinline__ void topk_list(const unsigned (&uk)[32], LAS int* list, LAS float* listr, LAS unsigned* listT, const GAS f32x4* sak, int lane) {
;     unsigned T = 0u;
;     ...
;         const unsigned cand = T | (1u << bit);
;         int c = 0;
; #pragma unroll
;         for (int rr = 0; rr < 32; ++rr) c += __builtin_popcountll(__builtin_amdgcn_ballot_w64(uk[rr] >= cand));
;         if (c >= 256) T = cand;
;         if (c == 256) break;
;     }
.LBB0_877:
	v_lshlrev_b32_e64 v54, v5, 1
	v_or_b32_e32 v54, v54, v4
	v_cmp_ge_u32_e32 vcc, v7, v54
	s_bcnt1_i32_b64 s0, vcc
	v_cmp_ge_u32_e32 vcc, v6, v54
	s_bcnt1_i32_b64 s1, vcc
	s_add_i32 s0, s0, s1
	v_cmp_ge_u32_e32 vcc, v3, v54
	s_bcnt1_i32_b64 s1, vcc
	s_add_i32 s0, s0, s1
	v_cmp_ge_u32_e32 vcc, v2, v54
	s_bcnt1_i32_b64 s1, vcc
	s_add_i32 s0, s0, s1
	s_cmpk_le_u32 s81, 0x100
	s_cbranch_scc1 .Lbis1_tail
	v_cmp_ge_u32_e32 vcc, v90, v54
	s_bcnt1_i32_b64 s1, vcc
	s_add_i32 s0, s0, s1
	v_cmp_ge_u32_e32 vcc, v89, v54
	s_bcnt1_i32_b64 s1, vcc
	s_add_i32 s0, s0, s1
	v_cmp_ge_u32_e32 vcc, v88, v54
	s_bcnt1_i32_b64 s1, vcc
	s_add_i32 s0, s0, s1
	v_cmp_ge_u32_e32 vcc, v87, v54
	s_bcnt1_i32_b64 s1, vcc
	s_add_i32 s0, s0, s1
	s_cmpk_le_u32 s81, 0x200
	s_cbranch_scc1 .Lbis1_tail
	v_cmp_ge_u32_e32 vcc, v120, v54
	s_bcnt1_i32_b64 s1, vcc
	s_add_i32 s0, s0, s1
	v_cmp_ge_u32_e32 vcc, v119, v54
	s_bcnt1_i32_b64 s1, vcc
	s_add_i32 s0, s0, s1
	v_cmp_ge_u32_e32 vcc, v118, v54
	s_bcnt1_i32_b64 s1, vcc
	s_add_i32 s0, s0, s1
	v_cmp_ge_u32_e32 vcc, v117, v54
	s_bcnt1_i32_b64 s1, vcc
	s_add_i32 s0, s0, s1
	s_cmpk_le_u32 s81, 0x300
	s_cbranch_scc1 .Lbis1_tail
	v_cmp_ge_u32_e32 vcc, v135, v54
	s_bcnt1_i32_b64 s1, vcc
	s_add_i32 s0, s0, s1
	v_cmp_ge_u32_e32 vcc, v134, v54
	s_bcnt1_i32_b64 s1, vcc
	s_add_i32 s0, s0, s1
	v_cmp_ge_u32_e32 vcc, v133, v54
	s_bcnt1_i32_b64 s1, vcc
	s_add_i32 s0, s0, s1
	v_cmp_ge_u32_e32 vcc, v123, v54
	s_bcnt1_i32_b64 s1, vcc
	s_add_i32 s0, s0, s1
	s_cmpk_le_u32 s81, 0x400
	s_cbranch_scc1 .Lbis1_tail
	v_cmp_ge_u32_e32 vcc, v139, v54
	s_bcnt1_i32_b64 s1, vcc
	s_add_i32 s0, s0, s1
	v_cmp_ge_u32_e32 vcc, v138, v54
	s_bcnt1_i32_b64 s1, vcc
	s_add_i32 s0, s0, s1
	v_cmp_ge_u32_e32 vcc, v137, v54
	s_bcnt1_i32_b64 s1, vcc
	s_add_i32 s0, s0, s1
	v_cmp_ge_u32_e32 vcc, v136, v54
	s_bcnt1_i32_b64 s1, vcc
	s_add_i32 s0, s0, s1
	s_cmpk_le_u32 s81, 0x500
	s_cbranch_scc1 .Lbis1_tail
	v_cmp_ge_u32_e32 vcc, v151, v54
	s_bcnt1_i32_b64 s1, vcc
	s_add_i32 s0, s0, s1
	v_cmp_ge_u32_e32 vcc, v149, v54
	s_bcnt1_i32_b64 s1, vcc
	s_add_i32 s0, s0, s1
	v_cmp_ge_u32_e32 vcc, v148, v54
	s_bcnt1_i32_b64 s1, vcc
	s_add_i32 s0, s0, s1
	v_cmp_ge_u32_e32 vcc, v147, v54
	s_bcnt1_i32_b64 s1, vcc
	s_add_i32 s0, s0, s1
	s_cmpk_le_u32 s81, 0x600
	s_cbranch_scc1 .Lbis1_tail
	v_cmp_ge_u32_e32 vcc, v163, v54
	s_bcnt1_i32_b64 s1, vcc
	s_add_i32 s0, s0, s1
	v_cmp_ge_u32_e32 vcc, v162, v54
	s_bcnt1_i32_b64 s1, vcc
	s_add_i32 s0, s0, s1
	v_cmp_ge_u32_e32 vcc, v161, v54
	s_bcnt1_i32_b64 s1, vcc
	s_add_i32 s0, s0, s1
	v_cmp_ge_u32_e32 vcc, v160, v54
	s_bcnt1_i32_b64 s1, vcc
	s_add_i32 s0, s0, s1
	s_cmpk_le_u32 s81, 0x700
	s_cbranch_scc1 .Lbis1_tail
	v_cmp_ge_u32_e32 vcc, v37, v54
	s_bcnt1_i32_b64 s1, vcc
	s_add_i32 s0, s0, s1
	v_cmp_ge_u32_e32 vcc, v36, v54
	s_bcnt1_i32_b64 s1, vcc
	s_add_i32 s0, s0, s1
	v_cmp_ge_u32_e32 vcc, v35, v54
	s_bcnt1_i32_b64 s1, vcc
	s_add_i32 s0, s0, s1
	v_cmp_ge_u32_e32 vcc, v34, v54
	s_bcnt1_i32_b64 s1, vcc
	s_add_i32 s0, s0, s1
; __device__ __forceinline__ void topk_list(const unsigned (&uk)[32], LAS int* list, LAS float* listr, LAS unsigned* listT, const GAS f32x4* sak, int lane) {
;     ...
;         if (c >= 256) T = cand;
;         if (c == 256) break;
;     }
;     int cgt = 0;
; #pragma unroll
;     for (int rr = 0; rr < 32; ++rr) cgt += __builtin_popcountll(__builtin_amdgcn_ballot_w64(uk[rr] > T));
;     const int need_eq = 256 - cgt;
;     int base = 0, eqseen = 0;
; #pragma unroll
;     for (int rr = 0; rr < 32; ++rr) {
;         const bool gt = uk[rr] > T, eq = uk[rr] == T;
;         const unsigned long long meq = __builtin_amdgcn_ballot_w64(eq);
;         const int erank = eqseen + (int)__builtin_amdgcn_mbcnt_hi((unsigned)(meq >> 32), __builtin_amdgcn_mbcnt_lo((unsigned)meq, 0u));
;         const bool sel = gt || (eq && erank < need_eq);
;         const unsigned long long ms = __builtin_amdgcn_ballot_w64(sel);
;         const int pos = base + (int)__builtin_amdgcn_mbcnt_hi((unsigned)(ms >> 32), __builtin_amdgcn_mbcnt_lo((unsigned)ms, 0u));
;         if (sel) { list[pos] = 64 * rr + lane; listT[((pos >> 5) * 4 + (pos & 3)) * 8 + ((pos >> 2) & 7)] = (unsigned)(64 * rr + lane) * 512u; }
.Lbis1_tail:
	s_cmpk_gt_u32 s0, 0xff
	s_cselect_b64 vcc, -1, 0
	s_cmpk_eq_i32 s0, 0x100
	v_cndmask_b32_e32 v4, v4, v54, vcc
	s_cselect_b64 s[0:1], -1, 0
	v_subrev_co_u32_e32 v5, vcc, 1, v5
	s_or_b64 s[0:1], s[0:1], vcc
	s_andn2_b64 vcc, exec, s[0:1]
	s_cbranch_vccnz .LBB0_877
	v_cmp_gt_u32_e32 vcc, v7, v4
	s_bcnt1_i32_b64 s0, vcc
	v_cmp_gt_u32_e32 vcc, v6, v4
	s_bcnt1_i32_b64 s1, vcc
	v_cmp_gt_u32_e32 vcc, v3, v4
	s_bcnt1_i32_b64 s2, vcc
	v_cmp_gt_u32_e32 vcc, v2, v4
	s_add_i32 s0, s0, s1
	s_bcnt1_i32_b64 s3, vcc
	v_cmp_gt_u32_e32 vcc, v90, v4
	s_add_i32 s0, s0, s2
	s_bcnt1_i32_b64 s64, vcc
	v_cmp_gt_u32_e32 vcc, v89, v4
	s_add_i32 s0, s0, s3
	s_bcnt1_i32_b64 s65, vcc
	v_cmp_gt_u32_e32 vcc, v88, v4
	s_add_i32 s0, s0, s64
	s_bcnt1_i32_b64 s66, vcc
	v_cmp_gt_u32_e32 vcc, v87, v4
	s_add_i32 s0, s0, s65
	s_bcnt1_i32_b64 s67, vcc
	v_cmp_gt_u32_e32 vcc, v120, v4
	s_add_i32 s64, s0, s66
	s_bcnt1_i32_b64 s68, vcc
	v_cmp_gt_u32_e32 vcc, v119, v4
	s_add_i32 s64, s64, s67
	s_bcnt1_i32_b64 s69, vcc
	v_cmp_gt_u32_e32 vcc, v118, v4
	s_add_i32 s64, s64, s68
	s_bcnt1_i32_b64 s70, vcc
	v_cmp_gt_u32_e32 vcc, v117, v4
	s_add_i32 s64, s64, s69
	s_bcnt1_i32_b64 s71, vcc
	v_cmp_gt_u32_e32 vcc, v135, v4
	s_add_i32 s64, s64, s70
	s_bcnt1_i32_b64 s74, vcc
	v_cmp_gt_u32_e32 vcc, v134, v4
	s_add_i32 s64, s64, s71
	s_bcnt1_i32_b64 s75, vcc
	v_cmp_gt_u32_e32 vcc, v133, v4
	s_add_i32 s64, s64, s74
	s_bcnt1_i32_b64 s76, vcc
	v_cmp_gt_u32_e32 vcc, v123, v4
	s_add_i32 s64, s64, s75
	s_bcnt1_i32_b64 s77, vcc
	v_cmp_gt_u32_e32 vcc, v139, v4
	s_add_i32 s64, s64, s76
	s_bcnt1_i32_b64 s78, vcc
	v_cmp_gt_u32_e32 vcc, v138, v4
	s_add_i32 s64, s64, s77
	s_bcnt1_i32_b64 s79, vcc
	v_cmp_gt_u32_e32 vcc, v137, v4
	s_add_i32 s64, s64, s78
	s_bcnt1_i32_b64 s80, vcc
	v_cmp_gt_u32_e32 vcc, v136, v4
	s_add_i32 s64, s64, s79
	s_bcnt1_i32_b64 s82, vcc
	v_cmp_gt_u32_e32 vcc, v151, v4
	s_add_i32 s64, s64, s80
	s_bcnt1_i32_b64 s83, vcc
	v_cmp_gt_u32_e32 vcc, v149, v4
	s_add_i32 s64, s64, s82
	s_bcnt1_i32_b64 s84, vcc
	v_cmp_gt_u32_e32 vcc, v148, v4
	s_add_i32 s64, s64, s83
	s_bcnt1_i32_b64 s85, vcc
	v_cmp_gt_u32_e32 vcc, v147, v4
	s_add_i32 s64, s64, s84
	s_bcnt1_i32_b64 s86, vcc
	v_cmp_gt_u32_e32 vcc, v163, v4
	s_add_i32 s64, s64, s85
	s_bcnt1_i32_b64 s87, vcc
	v_cmp_gt_u32_e32 vcc, v162, v4
	s_add_i32 s64, s64, s86
	s_bcnt1_i32_b64 s88, vcc
	v_cmp_gt_u32_e32 vcc, v161, v4
	s_add_i32 s64, s64, s87
	s_bcnt1_i32_b64 s89, vcc
	v_cmp_gt_u32_e32 vcc, v160, v4
	s_add_i32 s64, s64, s88
	s_bcnt1_i32_b64 s90, vcc
	v_cmp_gt_u32_e32 vcc, v37, v4
	s_add_i32 s64, s64, s89
	s_bcnt1_i32_b64 s91, vcc
	v_cmp_gt_u32_e32 vcc, v36, v4
	s_add_i32 s64, s64, s90
	s_bcnt1_i32_b64 s92, vcc
	v_cmp_gt_u32_e32 vcc, v35, v4
	s_add_i32 s64, s64, s91
	s_bcnt1_i32_b64 s93, vcc
	v_cmp_gt_u32_e32 vcc, v34, v4
	s_add_i32 s64, s64, s92
	s_bcnt1_i32_b64 s94, vcc
	s_add_i32 s64, s64, s93
	s_add_i32 s64, s64, s94
	v_cmp_le_u32_e64 s[60:61], v6, v4
	v_cmp_le_u32_e64 s[62:63], v7, v4
	v_cmp_le_u32_e64 s[58:59], v3, v4
	v_cmp_le_u32_e64 s[56:57], v2, v4
	v_cmp_le_u32_e64 s[54:55], v90, v4
	v_cmp_le_u32_e64 s[52:53], v89, v4
	v_cmp_le_u32_e64 s[50:51], v88, v4
	v_cmp_le_u32_e64 s[48:49], v87, v4
	v_cmp_le_u32_e64 s[46:47], v120, v4
	v_cmp_le_u32_e64 s[44:45], v119, v4
	v_cmp_le_u32_e64 s[42:43], v118, v4
	v_cmp_le_u32_e64 s[40:41], v117, v4
	v_cmp_le_u32_e64 s[38:39], v135, v4
	v_cmp_le_u32_e64 s[36:37], v134, v4
	v_cmp_le_u32_e64 s[34:35], v133, v4
	v_cmp_le_u32_e64 s[30:31], v123, v4
	v_cmp_le_u32_e64 s[28:29], v139, v4
	v_cmp_le_u32_e64 s[26:27], v138, v4
	v_cmp_le_u32_e64 s[24:25], v137, v4
	v_cmp_le_u32_e64 s[22:23], v136, v4
	v_cmp_le_u32_e64 s[20:21], v151, v4
	v_cmp_le_u32_e64 s[18:19], v149, v4
	v_cmp_le_u32_e64 s[16:17], v148, v4
	v_cmp_le_u32_e64 s[14:15], v147, v4
	v_cmp_le_u32_e64 s[12:13], v163, v4
	v_cmp_le_u32_e64 s[10:11], v162, v4
	v_cmp_le_u32_e64 s[8:9], v161, v4
	v_cmp_le_u32_e64 s[6:7], v160, v4
	v_cmp_le_u32_e64 s[4:5], v37, v4
	v_cmp_le_u32_e64 s[2:3], v36, v4
	v_cmp_le_u32_e64 s[0:1], v35, v4
	v_cmp_le_u32_e32 vcc, v34, v4
	s_sub_i32 s78, 0x100, s64
	v_cmp_eq_u32_e64 s[66:67], v7, v4
	s_mov_b64 s[68:69], -1
	s_and_saveexec_b64 s[64:65], s[62:63]
	v_mbcnt_lo_u32_b32 v5, s66, 0
	v_mbcnt_hi_u32_b32 v5, s67, v5
	v_cmp_gt_i32_e64 s[62:63], s78, v5
	s_and_b64 s[62:63], s[66:67], s[62:63]
	s_orn2_b64 s[68:69], s[62:63], exec
	s_or_b64 exec, exec, s[64:65]
	v_cndmask_b32_e64 v5, 0, 1, s[68:69]
	v_cmp_ne_u32_e64 s[64:65], 0, v5
	s_and_saveexec_b64 s[62:63], s[68:69]
	v_readlane_b32 s70, v254, 47
	v_readlane_b32 s76, v254, 51
	v_readlane_b32 s82, v254, 53
	v_readlane_b32 s71, v254, 48
	v_readlane_b32 s74, v254, 49
	v_readlane_b32 s77, v254, 52
	v_readlane_b32 s83, v254, 54
	s_cbranch_execz .LBB0_882
	v_mbcnt_lo_u32_b32 v5, s64, 0
	v_mbcnt_hi_u32_b32 v5, s65, v5
	v_lshl_add_u32 v7, v5, 2, s33
	ds_write_b32 v7, v124 offset:2048
	v_and_b32_e32 v7, 0x60, v5
	v_lshlrev_b32_e32 v54, 5, v5
	v_lshl_add_u32 v7, v7, 2, s33
	v_and_b32_e32 v54, 0x60, v54
	v_and_b32_e32 v5, 28, v5
	v_add3_u32 v5, v7, v54, v5
	ds_write_b32 v5, v9 offset:5120
